# stagger lever: waves 4-7 sleep 6 (384 cycles) at every MLA attention step, code padded to a 64-byte multiple
# speedup vs baseline: 1.0313x; 1.0034x over previous
.LBB0_786:
	v_readlane_b32 s6, v250, 0
	s_nop 0
	s_cmp_lt_u32 s6, 4
	s_cbranch_scc1 .Lmy_nostag
	s_sleep 6

.LBB0_793:
	s_nop 0
	s_nop 0
	s_nop 0
	s_nop 0
	s_nop 0
	s_nop 0
	s_nop 0
	s_nop 0
	s_nop 0
	s_nop 0
	s_and_b32 s2, s4, 0x7f
	s_lshl_b32 s3, s2, 3
	v_readlane_b32 s5, v250, 0
	s_add_i32 s3, s3, s5
	v_mov_b32_e32 v64, 0x4400
	v_mad_u64_u32 v[134:135], s[6:7], s3, v64, v[154:155]
	s_cmpk_gt_u32 s4, 0x7f
	s_mov_b64 s[8:9], -1
	s_cbranch_scc0 .LBB0_801
	v_readlane_b32 s6, v250, 15
	v_readlane_b32 s7, v250, 16
	s_andn2_b64 vcc, exec, s[6:7]
	s_cbranch_vccnz .LBB0_800
	s_lshl_b32 s2, s2, 6
	v_readlane_b32 s3, v252, 21
	s_add_u32 s8, s3, s2
	v_readlane_b32 s2, v252, 22
	s_addc_u32 s9, s2, 0
	s_mov_b32 s2, 0x100001
	s_branch .LBB0_797
